# strategy prologue de-serialisation: GEMM job prologue vmcnt(0) between LDS-DMA stages replaced by counted vmcnt(5)
# speedup vs baseline: 1.0224x; 1.0032x over previous
.LBB0_358:
	s_andn2_b64 vcc, exec, s[4:5]
	s_cbranch_vccnz .LBB0_299
	v_readlane_b32 s2, v254, 41
	v_readlane_b32 s3, v254, 42
	s_load_dwordx4 s[12:15], s[2:3], 0x118
	s_waitcnt lgkmcnt(0)
	s_add_u32 s4, s14, 0
	s_addc_u32 s5, s15, s30
	s_add_u32 s7, s4, s28
	s_addc_u32 s22, s5, 0
	s_add_u32 s4, s14, 0
	s_addc_u32 s5, s15, s31
	s_add_u32 s62, s4, s29
	s_addc_u32 s63, s5, 0
	s_lshl_b32 s10, s50, 1
	v_mad_u64_u32 v[200:201], s[4:5], s10, v226, v[196:197]
	v_mad_u64_u32 v[202:203], s[4:5], s10, v227, v[196:197]
	s_ashr_i32 s51, s50, 31
	s_lshl_b64 s[30:31], s[50:51], 9
	s_ashr_i32 s4, s0, 31
	s_mul_i32 s4, s30, s4
	s_mul_hi_u32 s5, s30, s0
	s_add_i32 s10, s5, s4
	s_lshr_b64 s[4:5], s[50:51], 23
	s_mul_i32 s5, s4, s0
	s_add_i32 s5, s10, s5
	s_ashr_i32 s10, s71, 31
	s_mul_i32 s10, s30, s10
	s_mul_hi_u32 s11, s30, s71
	s_lshr_b32 s39, s6, 6
	s_add_i32 s10, s11, s10
	s_mul_i32 s4, s4, s71
	s_lshr_b32 s38, s6, 8
	s_lshl_b64 s[28:29], s[50:51], 8
	s_lshl_b32 s72, s39, 10
	s_add_i32 s4, s10, s4
	s_mul_i32 s10, s30, s71
	s_add_u32 s10, s62, s10
	s_addc_u32 s11, s63, s4
	s_add_i32 s73, s72, 0
	s_add_i32 m0, s73, 0x10000
	s_mul_i32 s34, s30, s0
	global_load_lds_dwordx4 v200, s[10:11]
	s_add_i32 m0, s73, 0x12000
	s_add_u32 s4, s7, s34
	global_load_lds_dwordx4 v202, s[10:11]
	s_addc_u32 s5, s22, s5
	s_mov_b32 m0, s73
	s_add_i32 s78, s73, 0x2000
	global_load_lds_dwordx4 v200, s[4:5]
	s_mov_b32 m0, s78
	s_add_u32 s34, s10, s28
	global_load_lds_dwordx4 v202, s[4:5]
	s_addc_u32 s35, s11, s29
	s_add_i32 m0, s73, 0x14000
	v_mov_b32_e32 v201, v2
	v_mov_b32_e32 v203, v2
	global_load_lds_dwordx4 v200, s[34:35]
	s_add_i32 m0, s73, 0x16000
	s_waitcnt vmcnt(5)
	v_lshl_add_u64 v[12:13], s[34:35], 0, v[200:201]
	v_lshl_add_u64 v[14:15], s[34:35], 0, v[202:203]
	global_load_lds_dwordx4 v202, s[34:35]
	s_add_u32 s34, s4, s28
	s_addc_u32 s35, s5, s29
	s_add_i32 s79, s73, 0x4000
	s_mov_b32 m0, s79
	s_add_i32 s60, s73, 0x6000
	global_load_lds_dwordx4 v200, s[34:35]
	s_mov_b32 m0, s60
	v_lshl_add_u64 v[4:5], s[10:11], 0, v[200:201]
	global_load_lds_dwordx4 v202, s[34:35]
	v_lshl_add_u64 v[6:7], s[10:11], 0, v[202:203]
	v_lshl_add_u64 v[8:9], s[4:5], 0, v[200:201]
	v_lshl_add_u64 v[10:11], s[4:5], 0, v[202:203]
	s_cmp_lg_u32 s38, 1
	s_cbranch_scc1 .LBB0_361
	s_barrier
